# LayerNorm and post0 cross-lane reductions and rotary exchanges via DPP and permlane swaps instead of ds_bpermute ladders
# speedup vs baseline: 1.0612x; 1.0104x over previous
.LBB0_35:
	s_mov_b32 s44, 0
	s_add_i32 s2, s44, s76
	s_waitcnt vmcnt(0)
	v_mbcnt_lo_u32_b32 v0, -1, 0
	v_mbcnt_hi_u32_b32 v0, -1, v0
	s_add_i32 s18, s44, s69
	v_lshl_add_u32 v176, s2, 6, v0
	s_add_i32 s82, s44, s72
	v_readfirstlane_b32 s2, v176
	s_ashr_i32 s6, s2, 6
	v_readlane_b32 s4, v254, 11
	s_cmp_gt_u32 s4, 16
	s_cselect_b64 s[2:3], -1, 0
	s_cmp_lt_u32 s4, 17
	s_cselect_b64 s[10:11], -1, 0
	s_and_b64 s[4:5], s[10:11], exec
	s_mov_b32 s4, 0x12000
	s_cselect_b32 s4, s4, 0x10000
	s_lshl_b32 s5, s82, 3
	s_abs_i32 s7, s5
	v_cvt_f32_u32_e32 v1, s7
	s_mov_b32 s14, s18
	v_writelane_b32 v254, s14, 41
	s_lshl_b32 s13, s18, 3
	v_rcp_iflag_f32_e32 v1, v1
	v_writelane_b32 v254, s15, 42
	s_add_i32 s6, s6, s13
	s_sub_i32 s13, 0, s7
	v_mul_f32_e32 v1, 0x4f7ffffe, v1
	v_cvt_u32_f32_e32 v1, v1
	s_add_i32 s12, s4, s5
	s_add_i32 s12, s12, -1
	s_xor_b32 s5, s12, s5
	v_readfirstlane_b32 s14, v1
	s_mul_i32 s13, s13, s14
	s_mul_hi_u32 s13, s14, s13
	s_abs_i32 s12, s12
	s_add_i32 s14, s14, s13
	s_mul_hi_u32 s13, s12, s14
	s_mul_i32 s14, s13, s7
	s_sub_i32 s12, s12, s14
	s_ashr_i32 s5, s5, 31
	s_add_i32 s14, s13, 1
	s_sub_i32 s15, s12, s7
	s_cmp_ge_u32 s12, s7
	s_cselect_b32 s13, s14, s13
	s_cselect_b32 s12, s15, s12
	s_add_i32 s14, s13, 1
	s_cmp_ge_u32 s12, s7
	s_cselect_b32 s7, s14, s13
	s_xor_b32 s7, s7, s5
	s_sub_i32 s5, s7, s5
	s_mul_i32 s56, s5, s6
	s_add_i32 s5, s56, s5
	s_min_i32 s57, s5, s4
	s_cmp_ge_i32 s56, s57
	s_mov_b32 s54, 0x800000
	s_cbranch_scc1 .LBB0_134
	v_readlane_b32 s28, v254, 11
	s_cmp_lg_u32 s28, 21
	s_cselect_b64 s[6:7], -1, 0
	s_cmp_eq_u32 s28, 21
	s_cselect_b64 s[12:13], -1, 0
	s_cmp_eq_u32 s28, 17
	s_cselect_b64 s[14:15], -1, 0
	s_lshl_b64 s[4:5], s[44:45], 3
	s_add_u32 s22, s70, s4
	v_readlane_b32 s24, v253, 62
	s_addc_u32 s23, s71, s5
	v_readlane_b32 s26, v254, 0
	v_readlane_b32 s27, v254, 1
	s_add_u32 s4, s26, s44
	s_addc_u32 s5, s27, 0
	s_lshl_b64 s[18:19], s[44:45], 2
	v_readlane_b32 s25, v253, 63
	s_add_u32 s58, s24, s18
	s_addc_u32 s59, s25, s19
	s_cmp_eq_u32 s28, 10
	s_cselect_b64 s[18:19], -1, 0
	s_and_b64 s[20:21], s[18:19], exec
	s_movk_i32 s20, 0x400
	s_cselect_b32 s60, s20, 0x1000
	s_cselect_b32 s61, 0, 0xc00
	s_or_b64 s[12:13], s[18:19], s[12:13]
	s_and_b64 s[18:19], s[12:13], exec
	s_cselect_b32 s18, 64, 48
	s_add_u32 s18, s22, s18
	s_addc_u32 s19, s23, 0
	s_load_dwordx2 s[18:19], s[18:19], 0x0
	s_and_b64 s[10:11], s[10:11], exec
	s_cselect_b32 s20, 0, 0x1000
	v_and_b32_e32 v34, 63, v0
	v_lshlrev_b32_e32 v192, 5, v34
	s_waitcnt lgkmcnt(0)
	s_add_u32 s10, s18, s20
	s_addc_u32 s11, s19, 0
	s_and_b64 s[12:13], s[12:13], exec
	s_cselect_b32 s12, 0x48, 56
	s_add_u32 s12, s22, s12
	s_addc_u32 s13, s23, 0
	s_load_dwordx2 s[12:13], s[12:13], 0x0
	v_xor_b32_e32 v32, 1, v229
	v_cmp_lt_i32_e32 vcc, v32, v231
	v_mov_b32_e32 v33, v193
	v_mov_b32_e32 v62, 0
	s_waitcnt lgkmcnt(0)
	s_add_u32 s12, s12, s20
	s_addc_u32 s13, s13, 0
	global_load_dwordx4 v[0:3], v192, s[10:11] offset:16
	global_load_dwordx4 v[4:7], v192, s[10:11]
	global_load_dwordx4 v[8:11], v192, s[12:13] offset:16
	global_load_dwordx4 v[12:15], v192, s[12:13]
	global_load_dwordx4 v[16:19], v192, s[10:11] offset:2064
	global_load_dwordx4 v[20:23], v192, s[10:11] offset:2048
	global_load_dwordx4 v[24:27], v192, s[12:13] offset:2064
	global_load_dwordx4 v[28:31], v192, s[12:13] offset:2048
	v_cndmask_b32_e32 v32, v229, v32, vcc
	v_lshlrev_b32_e32 v109, 2, v32
	v_xor_b32_e32 v32, 2, v229
	v_cmp_lt_i32_e32 vcc, v32, v231
	s_cmp_eq_u32 s28, 6
	s_cselect_b64 s[10:11], -1, 0
	v_cndmask_b32_e32 v32, v229, v32, vcc
	v_lshlrev_b32_e32 v121, 2, v32
	v_xor_b32_e32 v32, 4, v229
	v_cmp_lt_i32_e32 vcc, v32, v231
	s_and_b64 s[12:13], s[10:11], exec
	s_mov_b32 s12, 0x44d4000
	v_cndmask_b32_e32 v32, v229, v32, vcc
	v_lshlrev_b32_e32 v122, 2, v32
	v_xor_b32_e32 v32, 8, v229
	v_cmp_lt_i32_e32 vcc, v32, v231
	s_cselect_b32 s12, s12, 0x459a000
	s_or_b64 s[10:11], s[10:11], s[14:15]
	v_cndmask_b32_e32 v32, v229, v32, vcc
	v_lshlrev_b32_e32 v123, 2, v32
	v_xor_b32_e32 v32, 16, v229
	v_cmp_lt_i32_e32 vcc, v32, v231
	s_add_u32 s62, s4, 0x38260000
	s_addc_u32 s63, s5, 0
	v_cndmask_b32_e32 v32, v229, v32, vcc
	v_lshlrev_b32_e32 v124, 2, v32
	v_xor_b32_e32 v32, 32, v229
	s_add_u32 s64, s4, 0x3d2e4000
	v_cmp_lt_i32_e32 vcc, v32, v231
	s_addc_u32 s65, s5, 0
	s_add_u32 s14, s4, s12
	v_cndmask_b32_e32 v32, v229, v32, vcc
	v_lshlrev_b32_e32 v125, 2, v32
	v_lshlrev_b32_e32 v32, 4, v34
	s_addc_u32 s15, s5, 0
	v_lshl_add_u64 v[32:33], s[4:5], 0, v[32:33]
	s_mov_b64 s[4:5], 0x4660000
	v_lshl_add_u64 v[110:111], v[32:33], 0, s[4:5]
	v_cmp_eq_u32_e32 vcc, 0, v34
	s_mov_b64 s[4:5], 0x16660000
	v_lshlrev_b32_e32 v108, 3, v34
	s_mov_b32 s68, -1
	s_and_b64 s[12:13], s[6:7], vcc
	v_lshl_add_u64 v[112:113], s[14:15], 0, v[192:193]
	v_lshl_add_u64 v[114:115], v[32:33], 0, s[4:5]
	v_mov_b32_e32 v63, v62
	v_mov_b32_e32 v54, v62
	v_mov_b32_e32 v55, v62
	v_mov_b32_e32 v60, v62
	v_mov_b32_e32 v61, v62
	v_mov_b32_e32 v52, v62
	v_mov_b32_e32 v53, v62
	v_mov_b32_e32 v58, v62
	v_mov_b32_e32 v59, v62
	v_mov_b32_e32 v50, v62
	v_mov_b32_e32 v51, v62
	v_mov_b32_e32 v56, v62
	v_mov_b32_e32 v57, v62
	v_mov_b32_e32 v48, v62
	v_mov_b32_e32 v49, v62
	v_mov_b32_e32 v38, v62
	v_mov_b32_e32 v39, v62
	v_mov_b32_e32 v46, v62
	v_mov_b32_e32 v47, v62
	v_mov_b32_e32 v36, v62
	v_mov_b32_e32 v37, v62
	v_mov_b32_e32 v44, v62
	v_mov_b32_e32 v45, v62
	v_mov_b32_e32 v34, v62
	v_mov_b32_e32 v35, v62
	v_mov_b32_e32 v42, v62
	v_mov_b32_e32 v43, v62
	v_mov_b32_e32 v32, v62
	v_mov_b32_e32 v33, v62
	v_mov_b32_e32 v40, v62
	v_mov_b32_e32 v41, v62
	s_branch .LBB0_38
	s_nop 0
	s_nop 0
	s_nop 0
	s_nop 0
	s_nop 0
	s_nop 0
	s_nop 0
	s_nop 0
	s_nop 0
	s_nop 0
	s_nop 0
	s_nop 0
	s_nop 0
	s_nop 0
	s_nop 0
	s_nop 0
	s_nop 0
	s_nop 0
	s_nop 0
	s_nop 0
	s_nop 0
	s_nop 0
	s_nop 0
	s_nop 0
	s_nop 0
	s_nop 0
	s_nop 0
	s_nop 0
	s_nop 0
	s_nop 0
	s_nop 0
	s_nop 0
	s_nop 0
	s_nop 0
	s_nop 0
	s_nop 0
	s_nop 0
	s_nop 0
	s_nop 0
	s_nop 0
	s_nop 0
	s_nop 0
	s_nop 0
	s_nop 0
	s_nop 0
	s_nop 0
	s_nop 0
	s_nop 0
	s_nop 0
	s_nop 0
	s_nop 0
	s_nop 0
	s_nop 0

.LBB0_54:
	s_waitcnt vmcnt(5)
	v_lshlrev_b32_e32 v88, 16, v68
	v_and_b32_e32 v89, 0xffff0000, v68
	v_add_f32_e32 v68, 0, v88
	v_add_f32_e32 v68, v68, v89
	v_lshlrev_b32_e32 v90, 16, v69
	v_and_b32_e32 v91, 0xffff0000, v69
	v_add_f32_e32 v68, v68, v90
	v_add_f32_e32 v68, v68, v91
	v_lshlrev_b32_e32 v92, 16, v70
	v_and_b32_e32 v93, 0xffff0000, v70
	v_add_f32_e32 v68, v68, v92
	v_add_f32_e32 v68, v68, v93
	v_lshlrev_b32_e32 v94, 16, v71
	v_and_b32_e32 v95, 0xffff0000, v71
	v_add_f32_e32 v68, v68, v94
	v_add_f32_e32 v68, v68, v95
	s_waitcnt vmcnt(4)
	v_lshlrev_b32_e32 v98, 16, v64
	v_and_b32_e32 v99, 0xffff0000, v64
	v_add_f32_e32 v64, v68, v98
	v_add_f32_e32 v64, v64, v99
	v_lshlrev_b32_e32 v100, 16, v65
	v_and_b32_e32 v101, 0xffff0000, v65
	v_add_f32_e32 v64, v64, v100
	v_add_f32_e32 v64, v64, v101
	v_lshlrev_b32_e32 v102, 16, v66
	v_and_b32_e32 v103, 0xffff0000, v66
	v_add_f32_e32 v64, v64, v102
	v_add_f32_e32 v64, v64, v103
	v_lshlrev_b32_e32 v118, 16, v67
	v_and_b32_e32 v119, 0xffff0000, v67
	v_add_f32_e32 v64, v64, v118
	v_add_f32_e32 v64, v64, v119
	s_ashr_i32 s23, s22, 31
	s_lshl_b64 s[20:21], s[22:23], 11
	s_nop 1
	v_add_f32_dpp v64, v64, v64 quad_perm:[1,0,3,2] row_mask:0xf bank_mask:0xf
	s_nop 1
	v_add_f32_dpp v64, v64, v64 quad_perm:[2,3,0,1] row_mask:0xf bank_mask:0xf
	s_nop 1
	v_add_f32_dpp v64, v64, v64 row_half_mirror row_mask:0xf bank_mask:0xf
	s_nop 1
	v_add_f32_dpp v64, v64, v64 row_mirror row_mask:0xf bank_mask:0xf
	v_mov_b32_e32 v65, v64
	v_mov_b32_e32 v96, v64
	s_nop 1
	v_permlane16_swap_b32_e32 v65, v96
	v_add_f32_e32 v96, v96, v65
	v_lshl_add_u64 v[64:65], v[110:111], 0, s[20:21]
	global_load_dwordx4 v[68:71], v[64:65], off
	s_nop 0
	global_load_dwordx4 v[64:67], v[64:65], off offset:1024
	v_mov_b32_e32 v97, v96
	s_nop 1
	v_permlane32_swap_b32_e32 v97, v96
	v_add_f32_e32 v96, v96, v97
	v_mul_f32_e32 v96, 0x3a800000, v96
	v_pk_add_f32 v[88:89], v[88:89], v[96:97] op_sel_hi:[1,0] neg_lo:[0,1] neg_hi:[0,1]
	v_pk_add_f32 v[90:91], v[90:91], v[96:97] op_sel_hi:[1,0] neg_lo:[0,1] neg_hi:[0,1]
	v_pk_mul_f32 v[126:127], v[88:89], v[88:89]
	v_pk_add_f32 v[92:93], v[92:93], v[96:97] op_sel_hi:[1,0] neg_lo:[0,1] neg_hi:[0,1]
	v_pk_mul_f32 v[128:129], v[90:91], v[90:91]
	v_pk_add_f32 v[94:95], v[94:95], v[96:97] op_sel_hi:[1,0] neg_lo:[0,1] neg_hi:[0,1]
	v_pk_add_f32 v[104:105], v[98:99], v[96:97] op_sel_hi:[1,0] neg_lo:[0,1] neg_hi:[0,1]
	v_pk_add_f32 v[106:107], v[100:101], v[96:97] op_sel_hi:[1,0] neg_lo:[0,1] neg_hi:[0,1]
	v_pk_add_f32 v[116:117], v[102:103], v[96:97] op_sel_hi:[1,0] neg_lo:[0,1] neg_hi:[0,1]
	v_pk_add_f32 v[118:119], v[118:119], v[96:97] op_sel_hi:[1,0] neg_lo:[0,1] neg_hi:[0,1]
	v_add_f32_e32 v97, v126, v127
	v_add_f32_e32 v97, v128, v97
	v_pk_mul_f32 v[130:131], v[92:93], v[92:93]
	v_add_f32_e32 v97, v129, v97
	v_add_f32_e32 v97, v130, v97
	v_pk_mul_f32 v[132:133], v[94:95], v[94:95]
	v_add_f32_e32 v97, v131, v97
	v_add_f32_e32 v97, v132, v97
	v_pk_mul_f32 v[98:99], v[104:105], v[104:105]
	v_add_f32_e32 v97, v133, v97
	v_add_f32_e32 v97, v98, v97
	v_pk_mul_f32 v[100:101], v[106:107], v[106:107]
	v_add_f32_e32 v97, v99, v97
	v_add_f32_e32 v97, v100, v97
	v_pk_mul_f32 v[102:103], v[116:117], v[116:117]
	v_add_f32_e32 v97, v101, v97
	v_add_f32_e32 v97, v102, v97
	v_pk_mul_f32 v[134:135], v[118:119], v[118:119]
	v_add_f32_e32 v97, v103, v97
	v_add_f32_e32 v97, v134, v97
	v_add_f32_e32 v97, v135, v97
	s_nop 1
	v_add_f32_dpp v97, v97, v97 quad_perm:[1,0,3,2] row_mask:0xf bank_mask:0xf
	s_nop 1
	v_add_f32_dpp v97, v97, v97 quad_perm:[2,3,0,1] row_mask:0xf bank_mask:0xf
	s_nop 1
	v_add_f32_dpp v97, v97, v97 row_half_mirror row_mask:0xf bank_mask:0xf
	s_nop 1
	v_add_f32_dpp v97, v97, v97 row_mirror row_mask:0xf bank_mask:0xf
	v_mov_b32_e32 v98, v97
	s_nop 1
	v_permlane16_swap_b32_e32 v98, v97
	v_add_f32_e32 v97, v97, v98
	v_mov_b32_e32 v98, v97
	s_nop 1
	v_permlane32_swap_b32_e32 v98, v97
	v_add_f32_e32 v97, v97, v98
	v_fmamk_f32 v97, v97, 0x3a800000, v225
	v_mul_f32_e32 v98, 0x4b800000, v97
	v_cmp_gt_f32_e32 vcc, s54, v97
	s_nop 1
	v_cndmask_b32_e32 v97, v97, v98, vcc
	v_rsq_f32_e32 v97, v97
	s_nop 0
	v_mul_f32_e32 v98, 0x45800000, v97
	v_cndmask_b32_e32 v120, v97, v98, vcc
	s_and_saveexec_b64 s[4:5], s[12:13]
	s_cbranch_execz .LBB0_56
	s_lshl_b64 s[52:53], s[52:53], 3
	s_add_u32 s52, s64, s52
	v_mov_b32_e32 v97, v120
	s_addc_u32 s53, s65, s53
	global_store_dwordx2 v193, v[96:97], s[52:53]

.LBB0_74:
	s_waitcnt vmcnt(5)
	s_nop 0
	v_lshlrev_b32_e32 v90, 16, v84
	v_and_b32_e32 v91, 0xffff0000, v84
	v_add_f32_e32 v84, 0, v90
	v_add_f32_e32 v88, v84, v91
	v_lshlrev_b32_e32 v84, 16, v85
	v_and_b32_e32 v85, 0xffff0000, v85
	v_add_f32_e32 v88, v88, v84
	v_add_f32_e32 v88, v88, v85
	v_lshlrev_b32_e32 v92, 16, v86
	v_and_b32_e32 v93, 0xffff0000, v86
	v_add_f32_e32 v86, v88, v92
	v_add_f32_e32 v88, v86, v93
	v_lshlrev_b32_e32 v86, 16, v87
	v_and_b32_e32 v87, 0xffff0000, v87
	v_add_f32_e32 v88, v88, v86
	v_add_f32_e32 v88, v88, v87
	s_waitcnt vmcnt(4)
	v_lshlrev_b32_e32 v94, 16, v80
	v_and_b32_e32 v95, 0xffff0000, v80
	v_add_f32_e32 v80, v88, v94
	v_add_f32_e32 v80, v80, v95
	v_lshlrev_b32_e32 v98, 16, v81
	v_and_b32_e32 v99, 0xffff0000, v81
	v_add_f32_e32 v80, v80, v98
	v_add_f32_e32 v80, v80, v99
	v_lshlrev_b32_e32 v100, 16, v82
	v_and_b32_e32 v101, 0xffff0000, v82
	v_add_f32_e32 v80, v80, v100
	v_add_f32_e32 v80, v80, v101
	v_lshlrev_b32_e32 v102, 16, v83
	v_and_b32_e32 v103, 0xffff0000, v83
	v_add_f32_e32 v80, v80, v102
	v_add_f32_e32 v80, v80, v103
	s_nop 1
	v_add_f32_dpp v80, v80, v80 quad_perm:[1,0,3,2] row_mask:0xf bank_mask:0xf
	s_nop 1
	v_add_f32_dpp v80, v80, v80 quad_perm:[2,3,0,1] row_mask:0xf bank_mask:0xf
	s_nop 1
	v_add_f32_dpp v80, v80, v80 row_half_mirror row_mask:0xf bank_mask:0xf
	s_nop 1
	v_add_f32_dpp v80, v80, v80 row_mirror row_mask:0xf bank_mask:0xf
	v_mov_b32_e32 v81, v80
	s_nop 1
	v_permlane16_swap_b32_e32 v81, v80
	v_add_f32_e32 v80, v80, v81
	v_mov_b32_e32 v81, v80
	s_nop 1
	v_permlane32_swap_b32_e32 v81, v80
	v_add_f32_e32 v80, v80, v81
	v_mul_f32_e32 v88, 0x3a800000, v80
	v_pk_add_f32 v[80:81], v[90:91], v[88:89] op_sel_hi:[1,0] neg_lo:[0,1] neg_hi:[0,1]
	v_pk_add_f32 v[82:83], v[84:85], v[88:89] op_sel_hi:[1,0] neg_lo:[0,1] neg_hi:[0,1]
	v_pk_mul_f32 v[90:91], v[80:81], v[80:81]
	v_pk_add_f32 v[84:85], v[92:93], v[88:89] op_sel_hi:[1,0] neg_lo:[0,1] neg_hi:[0,1]
	v_pk_add_f32 v[86:87], v[86:87], v[88:89] op_sel_hi:[1,0] neg_lo:[0,1] neg_hi:[0,1]
	v_pk_add_f32 v[96:97], v[94:95], v[88:89] op_sel_hi:[1,0] neg_lo:[0,1] neg_hi:[0,1]
	v_pk_add_f32 v[98:99], v[98:99], v[88:89] op_sel_hi:[1,0] neg_lo:[0,1] neg_hi:[0,1]
	v_pk_mul_f32 v[92:93], v[82:83], v[82:83]
	v_pk_add_f32 v[100:101], v[100:101], v[88:89] op_sel_hi:[1,0] neg_lo:[0,1] neg_hi:[0,1]
	v_pk_add_f32 v[102:103], v[102:103], v[88:89] op_sel_hi:[1,0] neg_lo:[0,1] neg_hi:[0,1]
	v_add_f32_e32 v89, v90, v91
	v_add_f32_e32 v89, v92, v89
	v_pk_mul_f32 v[94:95], v[84:85], v[84:85]
	v_add_f32_e32 v89, v93, v89
	v_add_f32_e32 v89, v94, v89
	v_pk_mul_f32 v[104:105], v[86:87], v[86:87]
	v_add_f32_e32 v89, v95, v89
	v_add_f32_e32 v89, v104, v89
	v_pk_mul_f32 v[106:107], v[96:97], v[96:97]
	v_add_f32_e32 v89, v105, v89
	v_add_f32_e32 v89, v106, v89
	v_pk_mul_f32 v[116:117], v[98:99], v[98:99]
	v_add_f32_e32 v89, v107, v89
	v_add_f32_e32 v89, v116, v89
	v_pk_mul_f32 v[118:119], v[100:101], v[100:101]
	v_add_f32_e32 v89, v117, v89
	v_add_f32_e32 v89, v118, v89
	v_pk_mul_f32 v[126:127], v[102:103], v[102:103]
	v_add_f32_e32 v89, v119, v89
	v_add_f32_e32 v89, v126, v89
	v_add_f32_e32 v89, v127, v89
	s_nop 1
	v_add_f32_dpp v89, v89, v89 quad_perm:[1,0,3,2] row_mask:0xf bank_mask:0xf
	s_nop 1
	v_add_f32_dpp v89, v89, v89 quad_perm:[2,3,0,1] row_mask:0xf bank_mask:0xf
	s_nop 1
	v_add_f32_dpp v89, v89, v89 row_half_mirror row_mask:0xf bank_mask:0xf
	s_nop 1
	v_add_f32_dpp v89, v89, v89 row_mirror row_mask:0xf bank_mask:0xf
	v_mov_b32_e32 v90, v89
	s_nop 1
	v_permlane16_swap_b32_e32 v90, v89
	v_add_f32_e32 v89, v89, v90
	v_mov_b32_e32 v90, v89
	s_nop 1
	v_permlane32_swap_b32_e32 v90, v89
	v_add_f32_e32 v89, v89, v90
	v_fmamk_f32 v89, v89, 0x3a800000, v225
	v_mul_f32_e32 v90, 0x4b800000, v89
	v_cmp_gt_f32_e32 vcc, s54, v89
	s_nop 1
	v_cndmask_b32_e32 v89, v89, v90, vcc
	v_rsq_f32_e32 v89, v89
	s_nop 0
	v_mul_f32_e32 v90, 0x45800000, v89
	v_cndmask_b32_e32 v104, v89, v90, vcc
	s_and_saveexec_b64 s[46:47], s[12:13]
	s_cbranch_execz .LBB0_76
	s_lshl_b64 s[42:43], s[42:43], 3
	s_add_u32 s42, s64, s42
	v_mov_b32_e32 v89, v104
	s_addc_u32 s43, s65, s43
	global_store_dwordx2 v193, v[88:89], s[42:43]

.LBB0_94:
	s_waitcnt vmcnt(3)
	s_nop 0
	v_lshlrev_b32_e32 v82, 16, v76
	v_and_b32_e32 v83, 0xffff0000, v76
	v_add_f32_e32 v76, 0, v82
	v_add_f32_e32 v80, v76, v83
	v_lshlrev_b32_e32 v76, 16, v77
	v_and_b32_e32 v77, 0xffff0000, v77
	v_add_f32_e32 v80, v80, v76
	v_add_f32_e32 v80, v80, v77
	v_lshlrev_b32_e32 v84, 16, v78
	v_and_b32_e32 v85, 0xffff0000, v78
	v_add_f32_e32 v78, v80, v84
	v_add_f32_e32 v80, v78, v85
	v_lshlrev_b32_e32 v78, 16, v79
	v_and_b32_e32 v79, 0xffff0000, v79
	v_add_f32_e32 v80, v80, v78
	v_add_f32_e32 v80, v80, v79
	s_waitcnt vmcnt(2)
	v_lshlrev_b32_e32 v86, 16, v72
	v_and_b32_e32 v87, 0xffff0000, v72
	v_add_f32_e32 v72, v80, v86
	v_add_f32_e32 v72, v72, v87
	v_lshlrev_b32_e32 v90, 16, v73
	v_and_b32_e32 v91, 0xffff0000, v73
	v_add_f32_e32 v72, v72, v90
	v_add_f32_e32 v72, v72, v91
	v_lshlrev_b32_e32 v92, 16, v74
	v_and_b32_e32 v93, 0xffff0000, v74
	v_add_f32_e32 v72, v72, v92
	v_add_f32_e32 v72, v72, v93
	v_lshlrev_b32_e32 v94, 16, v75
	v_and_b32_e32 v95, 0xffff0000, v75
	v_add_f32_e32 v72, v72, v94
	v_add_f32_e32 v72, v72, v95
	s_nop 1
	v_add_f32_dpp v72, v72, v72 quad_perm:[1,0,3,2] row_mask:0xf bank_mask:0xf
	s_nop 1
	v_add_f32_dpp v72, v72, v72 quad_perm:[2,3,0,1] row_mask:0xf bank_mask:0xf
	s_nop 1
	v_add_f32_dpp v72, v72, v72 row_half_mirror row_mask:0xf bank_mask:0xf
	s_nop 1
	v_add_f32_dpp v72, v72, v72 row_mirror row_mask:0xf bank_mask:0xf
	v_mov_b32_e32 v73, v72
	s_nop 1
	v_permlane16_swap_b32_e32 v73, v72
	v_add_f32_e32 v72, v72, v73
	v_mov_b32_e32 v73, v72
	s_nop 1
	v_permlane32_swap_b32_e32 v73, v72
	v_add_f32_e32 v72, v72, v73
	v_mul_f32_e32 v80, 0x3a800000, v72
	v_pk_add_f32 v[72:73], v[82:83], v[80:81] op_sel_hi:[1,0] neg_lo:[0,1] neg_hi:[0,1]
	v_pk_add_f32 v[74:75], v[76:77], v[80:81] op_sel_hi:[1,0] neg_lo:[0,1] neg_hi:[0,1]
	v_pk_mul_f32 v[82:83], v[72:73], v[72:73]
	v_pk_add_f32 v[76:77], v[84:85], v[80:81] op_sel_hi:[1,0] neg_lo:[0,1] neg_hi:[0,1]
	v_pk_add_f32 v[78:79], v[78:79], v[80:81] op_sel_hi:[1,0] neg_lo:[0,1] neg_hi:[0,1]
	v_pk_add_f32 v[88:89], v[86:87], v[80:81] op_sel_hi:[1,0] neg_lo:[0,1] neg_hi:[0,1]
	v_pk_add_f32 v[90:91], v[90:91], v[80:81] op_sel_hi:[1,0] neg_lo:[0,1] neg_hi:[0,1]
	v_pk_mul_f32 v[84:85], v[74:75], v[74:75]
	v_pk_add_f32 v[92:93], v[92:93], v[80:81] op_sel_hi:[1,0] neg_lo:[0,1] neg_hi:[0,1]
	v_pk_add_f32 v[94:95], v[94:95], v[80:81] op_sel_hi:[1,0] neg_lo:[0,1] neg_hi:[0,1]
	v_add_f32_e32 v81, v82, v83
	v_add_f32_e32 v81, v84, v81
	v_pk_mul_f32 v[86:87], v[76:77], v[76:77]
	v_add_f32_e32 v81, v85, v81
	v_add_f32_e32 v81, v86, v81
	v_pk_mul_f32 v[96:97], v[78:79], v[78:79]
	v_add_f32_e32 v81, v87, v81
	v_add_f32_e32 v81, v96, v81
	v_pk_mul_f32 v[98:99], v[88:89], v[88:89]
	v_add_f32_e32 v81, v97, v81
	v_add_f32_e32 v81, v98, v81
	v_pk_mul_f32 v[100:101], v[90:91], v[90:91]
	v_add_f32_e32 v81, v99, v81
	v_add_f32_e32 v81, v100, v81
	v_pk_mul_f32 v[102:103], v[92:93], v[92:93]
	v_add_f32_e32 v81, v101, v81
	v_add_f32_e32 v81, v102, v81
	v_pk_mul_f32 v[104:105], v[94:95], v[94:95]
	v_add_f32_e32 v81, v103, v81
	v_add_f32_e32 v81, v104, v81
	v_add_f32_e32 v81, v105, v81
	s_nop 1
	v_add_f32_dpp v81, v81, v81 quad_perm:[1,0,3,2] row_mask:0xf bank_mask:0xf
	s_nop 1
	v_add_f32_dpp v81, v81, v81 quad_perm:[2,3,0,1] row_mask:0xf bank_mask:0xf
	s_nop 1
	v_add_f32_dpp v81, v81, v81 row_half_mirror row_mask:0xf bank_mask:0xf
	s_nop 1
	v_add_f32_dpp v81, v81, v81 row_mirror row_mask:0xf bank_mask:0xf
	v_mov_b32_e32 v82, v81
	s_nop 1
	v_permlane16_swap_b32_e32 v82, v81
	v_add_f32_e32 v81, v81, v82
	v_mov_b32_e32 v82, v81
	s_nop 1
	v_permlane32_swap_b32_e32 v82, v81
	v_add_f32_e32 v81, v81, v82
	v_fmamk_f32 v81, v81, 0x3a800000, v225
	v_mul_f32_e32 v82, 0x4b800000, v81
	v_cmp_gt_f32_e32 vcc, s54, v81
	s_nop 1
	v_cndmask_b32_e32 v81, v81, v82, vcc
	v_rsq_f32_e32 v81, v81
	s_nop 0
	v_mul_f32_e32 v82, 0x45800000, v81
	v_cndmask_b32_e32 v96, v81, v82, vcc
	s_and_saveexec_b64 s[34:35], s[12:13]
	s_cbranch_execz .LBB0_96
	s_lshl_b64 s[30:31], s[30:31], 3
	s_add_u32 s30, s64, s30
	v_mov_b32_e32 v81, v96
	s_addc_u32 s31, s65, s31
	global_store_dwordx2 v193, v[80:81], s[30:31]

.LBB0_114:
	s_waitcnt vmcnt(1)
	s_nop 0
	v_lshlrev_b32_e32 v74, 16, v68
	v_and_b32_e32 v75, 0xffff0000, v68
	v_add_f32_e32 v68, 0, v74
	v_add_f32_e32 v72, v68, v75
	v_lshlrev_b32_e32 v68, 16, v69
	v_and_b32_e32 v69, 0xffff0000, v69
	v_add_f32_e32 v72, v72, v68
	v_add_f32_e32 v72, v72, v69
	v_lshlrev_b32_e32 v76, 16, v70
	v_and_b32_e32 v77, 0xffff0000, v70
	v_add_f32_e32 v70, v72, v76
	v_add_f32_e32 v72, v70, v77
	v_lshlrev_b32_e32 v70, 16, v71
	v_and_b32_e32 v71, 0xffff0000, v71
	v_add_f32_e32 v72, v72, v70
	v_add_f32_e32 v72, v72, v71
	s_waitcnt vmcnt(0)
	v_lshlrev_b32_e32 v78, 16, v64
	v_and_b32_e32 v79, 0xffff0000, v64
	v_add_f32_e32 v64, v72, v78
	v_add_f32_e32 v64, v64, v79
	v_lshlrev_b32_e32 v82, 16, v65
	v_and_b32_e32 v83, 0xffff0000, v65
	v_add_f32_e32 v64, v64, v82
	v_add_f32_e32 v64, v64, v83
	v_lshlrev_b32_e32 v84, 16, v66
	v_and_b32_e32 v85, 0xffff0000, v66
	v_add_f32_e32 v64, v64, v84
	v_add_f32_e32 v64, v64, v85
	v_lshlrev_b32_e32 v86, 16, v67
	v_and_b32_e32 v87, 0xffff0000, v67
	v_add_f32_e32 v64, v64, v86
	v_add_f32_e32 v64, v64, v87
	s_nop 1
	v_add_f32_dpp v64, v64, v64 quad_perm:[1,0,3,2] row_mask:0xf bank_mask:0xf
	s_nop 1
	v_add_f32_dpp v64, v64, v64 quad_perm:[2,3,0,1] row_mask:0xf bank_mask:0xf
	s_nop 1
	v_add_f32_dpp v64, v64, v64 row_half_mirror row_mask:0xf bank_mask:0xf
	s_nop 1
	v_add_f32_dpp v64, v64, v64 row_mirror row_mask:0xf bank_mask:0xf
	v_mov_b32_e32 v65, v64
	s_nop 1
	v_permlane16_swap_b32_e32 v65, v64
	v_add_f32_e32 v64, v64, v65
	v_mov_b32_e32 v65, v64
	s_nop 1
	v_permlane32_swap_b32_e32 v65, v64
	v_add_f32_e32 v64, v64, v65
	v_mul_f32_e32 v72, 0x3a800000, v64
	v_pk_add_f32 v[64:65], v[74:75], v[72:73] op_sel_hi:[1,0] neg_lo:[0,1] neg_hi:[0,1]
	v_pk_add_f32 v[66:67], v[68:69], v[72:73] op_sel_hi:[1,0] neg_lo:[0,1] neg_hi:[0,1]
	v_pk_mul_f32 v[74:75], v[64:65], v[64:65]
	v_pk_add_f32 v[68:69], v[76:77], v[72:73] op_sel_hi:[1,0] neg_lo:[0,1] neg_hi:[0,1]
	v_pk_add_f32 v[70:71], v[70:71], v[72:73] op_sel_hi:[1,0] neg_lo:[0,1] neg_hi:[0,1]
	v_pk_add_f32 v[80:81], v[78:79], v[72:73] op_sel_hi:[1,0] neg_lo:[0,1] neg_hi:[0,1]
	v_pk_add_f32 v[82:83], v[82:83], v[72:73] op_sel_hi:[1,0] neg_lo:[0,1] neg_hi:[0,1]
	v_pk_mul_f32 v[76:77], v[66:67], v[66:67]
	v_pk_add_f32 v[84:85], v[84:85], v[72:73] op_sel_hi:[1,0] neg_lo:[0,1] neg_hi:[0,1]
	v_pk_add_f32 v[86:87], v[86:87], v[72:73] op_sel_hi:[1,0] neg_lo:[0,1] neg_hi:[0,1]
	v_add_f32_e32 v73, v74, v75
	v_add_f32_e32 v73, v76, v73
	v_pk_mul_f32 v[78:79], v[68:69], v[68:69]
	v_add_f32_e32 v73, v77, v73
	v_add_f32_e32 v73, v78, v73
	v_pk_mul_f32 v[88:89], v[70:71], v[70:71]
	v_add_f32_e32 v73, v79, v73
	v_add_f32_e32 v73, v88, v73
	v_pk_mul_f32 v[90:91], v[80:81], v[80:81]
	v_add_f32_e32 v73, v89, v73
	v_add_f32_e32 v73, v90, v73
	v_pk_mul_f32 v[92:93], v[82:83], v[82:83]
	v_add_f32_e32 v73, v91, v73
	v_add_f32_e32 v73, v92, v73
	v_pk_mul_f32 v[94:95], v[84:85], v[84:85]
	v_add_f32_e32 v73, v93, v73
	v_add_f32_e32 v73, v94, v73
	v_pk_mul_f32 v[96:97], v[86:87], v[86:87]
	v_add_f32_e32 v73, v95, v73
	v_add_f32_e32 v73, v96, v73
	v_add_f32_e32 v73, v97, v73
	s_nop 1
	v_add_f32_dpp v73, v73, v73 quad_perm:[1,0,3,2] row_mask:0xf bank_mask:0xf
	s_nop 1
	v_add_f32_dpp v73, v73, v73 quad_perm:[2,3,0,1] row_mask:0xf bank_mask:0xf
	s_nop 1
	v_add_f32_dpp v73, v73, v73 row_half_mirror row_mask:0xf bank_mask:0xf
	s_nop 1
	v_add_f32_dpp v73, v73, v73 row_mirror row_mask:0xf bank_mask:0xf
	v_mov_b32_e32 v74, v73
	s_nop 1
	v_permlane16_swap_b32_e32 v74, v73
	v_add_f32_e32 v73, v73, v74
	v_mov_b32_e32 v74, v73
	s_nop 1
	v_permlane32_swap_b32_e32 v74, v73
	v_add_f32_e32 v73, v73, v74
	v_fmamk_f32 v73, v73, 0x3a800000, v225
	v_mul_f32_e32 v74, 0x4b800000, v73
	v_cmp_gt_f32_e32 vcc, s54, v73
	s_nop 1
	v_cndmask_b32_e32 v73, v73, v74, vcc
	v_rsq_f32_e32 v73, v73
	s_nop 0
	v_mul_f32_e32 v74, 0x45800000, v73
	v_cndmask_b32_e32 v88, v73, v74, vcc
	s_and_saveexec_b64 s[24:25], s[12:13]
	s_cbranch_execz .LBB0_116
	s_lshl_b64 s[22:23], s[22:23], 3
	s_add_u32 s22, s64, s22
	v_mov_b32_e32 v73, v88
	s_addc_u32 s23, s65, s23
	global_store_dwordx2 v193, v[72:73], s[22:23]

.LBB0_144:
	s_or_b64 exec, exec, s[8:9]
	s_waitcnt vmcnt(1)
	v_lshlrev_b32_e32 v68, 16, v55
	v_and_b32_e32 v69, 0xffff0000, v55
	s_mov_b32 s8, 0x3d372713
	v_pk_mul_f32 v[70:71], v[68:69], s[8:9] op_sel_hi:[1,0]
	s_mov_b32 s12, 0x3f4c422a
	v_pk_mul_f32 v[70:71], v[70:71], v[68:69]
	s_mov_b32 s1, 0x800000
	v_pk_fma_f32 v[70:71], v[70:71], v[68:69], v[68:69]
	v_pk_mul_f32 v[68:69], v[68:69], 0.5 op_sel_hi:[1,0]
	v_pk_mul_f32 v[70:71], v[70:71], s[12:13] op_sel_hi:[1,0]
	s_nop 0
	v_mul_f32_e64 v55, |v70|, -2.0
	v_mul_f32_e32 v55, 0x3fb8aa3b, v55
	v_exp_f32_e32 v80, v55
	v_mul_f32_e64 v55, |v71|, -2.0
	v_mul_f32_e32 v55, 0x3fb8aa3b, v55
	v_exp_f32_e32 v81, v55
	v_add_f32_e32 v55, 1.0, v80
	v_rcp_f32_e32 v82, v55
	v_cmp_gt_f32_e32 vcc, 0, v71
	v_add_f32_e32 v55, 1.0, v81
	v_rcp_f32_e32 v83, v55
	v_pk_add_f32 v[80:81], v[80:81], 1.0 op_sel_hi:[1,0] neg_lo:[1,0] neg_hi:[1,0]
	s_nop 0
	v_pk_mul_f32 v[80:81], v[80:81], v[82:83]
	v_lshlrev_b32_e32 v82, 16, v54
	v_and_b32_e32 v83, 0xffff0000, v54
	v_pk_mul_f32 v[84:85], v[82:83], s[8:9] op_sel_hi:[1,0]
	v_cndmask_b32_e64 v55, v81, -v81, vcc
	v_pk_mul_f32 v[84:85], v[84:85], v[82:83]
	v_cmp_gt_f32_e32 vcc, 0, v70
	v_pk_fma_f32 v[84:85], v[84:85], v[82:83], v[82:83]
	v_pk_mul_f32 v[82:83], v[82:83], 0.5 op_sel_hi:[1,0]
	v_pk_mul_f32 v[84:85], v[84:85], s[12:13] op_sel_hi:[1,0]
	s_nop 0
	v_mul_f32_e64 v54, |v84|, -2.0
	v_mul_f32_e32 v54, 0x3fb8aa3b, v54
	v_exp_f32_e32 v86, v54
	v_mul_f32_e64 v54, |v85|, -2.0
	v_mul_f32_e32 v54, 0x3fb8aa3b, v54
	v_exp_f32_e32 v87, v54
	v_add_f32_e32 v70, 1.0, v86
	v_rcp_f32_e32 v70, v70
	v_cndmask_b32_e64 v54, v80, -v80, vcc
	v_add_f32_e32 v71, 1.0, v87
	v_rcp_f32_e32 v71, v71
	v_pk_add_f32 v[86:87], v[86:87], 1.0 op_sel_hi:[1,0] neg_lo:[1,0] neg_hi:[1,0]
	v_cmp_gt_f32_e32 vcc, 0, v85
	v_pk_add_f32 v[54:55], v[54:55], 1.0 op_sel_hi:[1,0]
	v_pk_mul_f32 v[70:71], v[86:87], v[70:71]
	v_lshlrev_b32_e32 v86, 16, v53
	v_and_b32_e32 v87, 0xffff0000, v53
	v_pk_mul_f32 v[88:89], v[86:87], s[8:9] op_sel_hi:[1,0]
	v_cndmask_b32_e64 v71, v71, -v71, vcc
	v_pk_mul_f32 v[88:89], v[88:89], v[86:87]
	v_cmp_gt_f32_e32 vcc, 0, v84
	v_pk_fma_f32 v[88:89], v[88:89], v[86:87], v[86:87]
	v_pk_mul_f32 v[86:87], v[86:87], 0.5 op_sel_hi:[1,0]
	v_pk_mul_f32 v[88:89], v[88:89], s[12:13] op_sel_hi:[1,0]
	v_cndmask_b32_e64 v70, v70, -v70, vcc
	v_mul_f32_e64 v53, |v88|, -2.0
	v_mul_f32_e32 v53, 0x3fb8aa3b, v53
	v_exp_f32_e32 v90, v53
	v_mul_f32_e64 v53, |v89|, -2.0
	v_mul_f32_e32 v53, 0x3fb8aa3b, v53
	v_exp_f32_e32 v91, v53
	v_add_f32_e32 v53, 1.0, v90
	v_rcp_f32_e32 v84, v53
	v_cmp_gt_f32_e32 vcc, 0, v89
	v_add_f32_e32 v53, 1.0, v91
	v_rcp_f32_e32 v85, v53
	v_pk_add_f32 v[90:91], v[90:91], 1.0 op_sel_hi:[1,0] neg_lo:[1,0] neg_hi:[1,0]
	v_pk_add_f32 v[70:71], v[70:71], 1.0 op_sel_hi:[1,0]
	v_pk_mul_f32 v[80:81], v[68:69], v[54:55]
	v_pk_mul_f32 v[84:85], v[90:91], v[84:85]
	v_lshlrev_b32_e32 v90, 16, v52
	v_and_b32_e32 v91, 0xffff0000, v52
	v_pk_mul_f32 v[94:95], v[90:91], s[8:9] op_sel_hi:[1,0]
	v_cndmask_b32_e64 v53, v85, -v85, vcc
	v_pk_mul_f32 v[94:95], v[94:95], v[90:91]
	v_cmp_gt_f32_e32 vcc, 0, v88
	v_pk_fma_f32 v[94:95], v[94:95], v[90:91], v[90:91]
	v_pk_mul_f32 v[90:91], v[90:91], 0.5 op_sel_hi:[1,0]
	v_pk_mul_f32 v[94:95], v[94:95], s[12:13] op_sel_hi:[1,0]
	v_pk_mul_f32 v[92:93], v[82:83], v[70:71]
	v_mul_f32_e64 v52, |v94|, -2.0
	v_mul_f32_e32 v52, 0x3fb8aa3b, v52
	v_exp_f32_e32 v96, v52
	v_mul_f32_e64 v52, |v95|, -2.0
	v_mul_f32_e32 v52, 0x3fb8aa3b, v52
	v_exp_f32_e32 v97, v52
	v_add_f32_e32 v79, 1.0, v96
	v_cndmask_b32_e64 v52, v84, -v84, vcc
	v_rcp_f32_e32 v84, v79
	v_add_f32_e32 v79, 1.0, v97
	v_rcp_f32_e32 v85, v79
	v_pk_add_f32 v[96:97], v[96:97], 1.0 op_sel_hi:[1,0] neg_lo:[1,0] neg_hi:[1,0]
	v_cmp_gt_f32_e32 vcc, 0, v95
	v_pk_add_f32 v[52:53], v[52:53], 1.0 op_sel_hi:[1,0]
	v_pk_mul_f32 v[84:85], v[96:97], v[84:85]
	v_pk_mul_f32 v[88:89], v[86:87], v[52:53]
	v_cndmask_b32_e64 v85, v85, -v85, vcc
	v_cmp_gt_f32_e32 vcc, 0, v94
	s_nop 1
	v_cndmask_b32_e64 v84, v84, -v84, vcc
	v_pk_add_f32 v[84:85], v[84:85], 1.0 op_sel_hi:[1,0]
	s_nop 0
	v_pk_mul_f32 v[94:95], v[90:91], v[84:85]
	s_nop 0
	v_add_f32_e32 v79, 0, v94
	v_add_f32_e32 v79, v95, v79
	v_add_f32_e32 v79, v88, v79
	v_add_f32_e32 v79, v89, v79
	v_add_f32_e32 v79, v92, v79
	v_add_f32_e32 v79, v93, v79
	v_add_f32_e32 v79, v80, v79
	v_add_f32_e32 v79, v81, v79
	s_nop 1
	v_add_f32_dpp v79, v79, v79 quad_perm:[1,0,3,2] row_mask:0xf bank_mask:0xf
	s_nop 1
	v_add_f32_dpp v79, v79, v79 quad_perm:[2,3,0,1] row_mask:0xf bank_mask:0xf
	s_nop 1
	v_add_f32_dpp v79, v79, v79 row_half_mirror row_mask:0xf bank_mask:0xf
	s_nop 1
	v_add_f32_dpp v79, v79, v79 row_mirror row_mask:0xf bank_mask:0xf
	v_mov_b32_e32 v80, v79
	s_nop 1
	v_permlane16_swap_b32_e32 v80, v79
	v_add_f32_e32 v79, v79, v80
	v_mov_b32_e32 v80, v79
	s_nop 1
	v_permlane32_swap_b32_e32 v80, v79
	v_add_f32_e32 v79, v79, v80
	v_mul_f32_e32 v80, 0x3b000000, v79
	v_pk_fma_f32 v[84:85], v[90:91], v[84:85], v[80:81] op_sel_hi:[1,1,0] neg_lo:[0,0,1] neg_hi:[0,0,1]
	v_pk_fma_f32 v[52:53], v[86:87], v[52:53], v[80:81] op_sel_hi:[1,1,0] neg_lo:[0,0,1] neg_hi:[0,0,1]
	v_pk_mul_f32 v[88:89], v[84:85], v[84:85]
	v_pk_mul_f32 v[86:87], v[52:53], v[52:53]
	v_add_f32_e32 v79, v88, v89
	v_pk_fma_f32 v[70:71], v[82:83], v[70:71], v[80:81] op_sel_hi:[1,1,0] neg_lo:[0,0,1] neg_hi:[0,0,1]
	v_add_f32_e32 v79, v86, v79
	v_pk_mul_f32 v[82:83], v[70:71], v[70:71]
	v_add_f32_e32 v79, v87, v79
	v_pk_fma_f32 v[54:55], v[68:69], v[54:55], v[80:81] op_sel_hi:[1,1,0] neg_lo:[0,0,1] neg_hi:[0,0,1]
	v_add_f32_e32 v79, v82, v79
	v_pk_mul_f32 v[68:69], v[54:55], v[54:55]
	v_add_f32_e32 v79, v83, v79
	v_add_f32_e32 v68, v68, v79
	v_add_f32_e32 v68, v69, v68
	s_nop 1
	v_add_f32_dpp v68, v68, v68 quad_perm:[1,0,3,2] row_mask:0xf bank_mask:0xf
	s_nop 1
	v_add_f32_dpp v68, v68, v68 quad_perm:[2,3,0,1] row_mask:0xf bank_mask:0xf
	s_nop 1
	v_add_f32_dpp v68, v68, v68 row_half_mirror row_mask:0xf bank_mask:0xf
	s_nop 1
	v_add_f32_dpp v68, v68, v68 row_mirror row_mask:0xf bank_mask:0xf
	v_mov_b32_e32 v69, v68
	s_nop 1
	v_permlane16_swap_b32_e32 v69, v68
	v_add_f32_e32 v68, v68, v69
	v_mov_b32_e32 v69, v68
	s_nop 1
	v_permlane32_swap_b32_e32 v69, v68
	v_add_f32_e32 v68, v68, v69
	v_fmamk_f32 v68, v68, 0x3b000000, v225
	v_mul_f32_e32 v69, 0x4b800000, v68
	v_cmp_gt_f32_e32 vcc, s1, v68
	s_nop 1
	v_cndmask_b32_e32 v68, v68, v69, vcc
	v_rsq_f32_e32 v68, v68
	s_nop 0
	v_mul_f32_e32 v69, 0x45800000, v68
	v_cndmask_b32_e32 v68, v68, v69, vcc
	v_pk_mul_f32 v[52:53], v[52:53], v[68:69] op_sel_hi:[1,0]
	v_pk_mul_f32 v[80:81], v[84:85], v[68:69] op_sel_hi:[1,0]
	v_pk_fma_f32 v[82:83], v[10:11], v[52:53], v[14:15]
	v_pk_mul_f32 v[52:53], v[70:71], v[68:69] op_sel_hi:[1,0]
	v_pk_fma_f32 v[80:81], v[8:9], v[80:81], v[12:13]
	v_pk_fma_f32 v[70:71], v[0:1], v[52:53], v[4:5]
	v_pk_mul_f32 v[52:53], v[54:55], v[68:69] op_sel_hi:[1,0]
	v_cvt_pk_bf16_f32 v54, v70, v71
	v_pk_fma_f32 v[68:69], v[2:3], v[52:53], v[6:7]
	v_cvt_pk_bf16_f32 v52, v80, v81
	v_cvt_pk_bf16_f32 v53, v82, v83
	v_cvt_pk_bf16_f32 v55, v68, v69
	global_store_dwordx4 v[66:67], v[52:55], off
	s_and_saveexec_b64 s[12:13], s[4:5]
	s_cbranch_execz .LBB0_162
	v_lshlrev_b32_e32 v52, 16, v48
	v_and_b32_e32 v53, 0xffff0000, v48
	v_pk_mul_f32 v[54:55], v[52:53], v[52:53]
	v_lshlrev_b32_e32 v48, 16, v49
	v_and_b32_e32 v49, 0xffff0000, v49
	v_pk_mul_f32 v[66:67], v[48:49], v[48:49]
	v_add_f32_e32 v54, v54, v55
	v_lshlrev_b32_e32 v68, 16, v50
	v_and_b32_e32 v69, 0xffff0000, v50
	v_add_f32_e32 v54, v66, v54
	v_pk_mul_f32 v[70:71], v[68:69], v[68:69]
	v_add_f32_e32 v54, v67, v54
	v_lshlrev_b32_e32 v50, 16, v51
	v_and_b32_e32 v51, 0xffff0000, v51
	v_add_f32_e32 v54, v70, v54
	v_pk_mul_f32 v[80:81], v[50:51], v[50:51]
	v_add_f32_e32 v54, v71, v54
	v_lshlrev_b32_e32 v82, 16, v44
	v_and_b32_e32 v83, 0xffff0000, v44
	v_add_f32_e32 v54, v80, v54
	v_pk_mul_f32 v[84:85], v[82:83], v[82:83]
	v_add_f32_e32 v54, v81, v54
	v_lshlrev_b32_e32 v86, 16, v45
	v_and_b32_e32 v87, 0xffff0000, v45
	v_add_f32_e32 v54, v84, v54
	v_pk_mul_f32 v[44:45], v[86:87], v[86:87]
	v_add_f32_e32 v54, v85, v54
	v_lshlrev_b32_e32 v88, 16, v46
	v_and_b32_e32 v89, 0xffff0000, v46
	v_add_f32_e32 v44, v44, v54
	v_pk_mul_f32 v[90:91], v[88:89], v[88:89]
	v_add_f32_e32 v44, v45, v44
	v_lshlrev_b32_e32 v92, 16, v47
	v_and_b32_e32 v93, 0xffff0000, v47
	v_add_f32_e32 v44, v90, v44
	v_pk_mul_f32 v[46:47], v[92:93], v[92:93]
	v_add_f32_e32 v44, v91, v44
	v_add_f32_e32 v44, v46, v44
	v_add_f32_e32 v44, v47, v44
	s_mov_b32 s9, 0x800000
	s_mul_hi_i32 s1, s0, 0x38e38e39
	s_lshr_b32 s8, s1, 31
	s_ashr_i32 s1, s1, 9
	s_nop 1
	v_add_f32_dpp v44, v44, v44 quad_perm:[1,0,3,2] row_mask:0xf bank_mask:0xf
	s_add_i32 s1, s1, s8
	s_mulk_i32 s1, 0x900
	s_sub_i32 s1, s0, s1
	s_cmpk_gt_i32 s1, 0xff
	s_nop 1
	v_add_f32_dpp v44, v44, v44 quad_perm:[2,3,0,1] row_mask:0xf bank_mask:0xf
	s_nop 1
	v_add_f32_dpp v44, v44, v44 row_half_mirror row_mask:0xf bank_mask:0xf
	v_fmamk_f32 v44, v44, 0x3c000000, v225
	v_mul_f32_e32 v45, 0x4b800000, v44
	v_cmp_gt_f32_e32 vcc, s9, v44
	s_nop 1
	v_cndmask_b32_e32 v44, v44, v45, vcc
	v_rsq_f32_e32 v44, v44
	s_nop 0
	v_mul_f32_e32 v45, 0x45800000, v44
	v_cndmask_b32_e32 v70, v44, v45, vcc
	v_pk_mul_f32 v[44:45], v[70:71], v[52:53] op_sel_hi:[0,1]
	v_pk_mul_f32 v[52:53], v[28:29], v[44:45]
	v_pk_mul_f32 v[44:45], v[70:71], v[48:49] op_sel_hi:[0,1]
	v_pk_mul_f32 v[54:55], v[30:31], v[44:45]
	v_pk_mul_f32 v[44:45], v[70:71], v[68:69] op_sel_hi:[0,1]
	s_cselect_b64 vcc, -1, 0
	s_add_i32 s8, s1, 0xffffff00
	v_pk_mul_f32 v[66:67], v[24:25], v[44:45]
	v_pk_mul_f32 v[44:45], v[70:71], v[50:51] op_sel_hi:[0,1]
	v_pk_mul_f32 v[48:49], v[70:71], v[88:89] op_sel_hi:[0,1]
	s_and_b32 s9, s1, 63
	s_ashr_i32 s8, s8, 6
	v_pk_mul_f32 v[68:69], v[26:27], v[44:45]
	v_pk_mul_f32 v[44:45], v[70:71], v[82:83] op_sel_hi:[0,1]
	v_pk_mul_f32 v[46:47], v[70:71], v[86:87] op_sel_hi:[0,1]
	v_pk_mul_f32 v[50:51], v[16:17], v[48:49]
	v_pk_mul_f32 v[48:49], v[70:71], v[92:93] op_sel_hi:[0,1]
	v_mov_b32_e32 v70, s9
	v_mov_b32_e32 v71, s8
	v_cndmask_b32_e64 v70, v70, v71, s[6:7]
	v_mov_b32_dpp v80, v52 quad_perm:[2,3,0,1] row_mask:0xf bank_mask:0xf
	v_mov_b32_dpp v79, v53 quad_perm:[2,3,0,1] row_mask:0xf bank_mask:0xf
	v_lshlrev_b32_e32 v70, 5, v70
	v_cndmask_b32_e32 v70, 0, v70, vcc
	v_ashrrev_i32_e32 v71, 31, v70
	v_pk_mul_f32 v[44:45], v[20:21], v[44:45]
	v_pk_mul_f32 v[46:47], v[22:23], v[46:47]
	v_pk_mul_f32 v[48:49], v[18:19], v[48:49]
	s_cmpk_lt_i32 s1, 0x100
	v_lshl_add_u64 v[70:71], v[70:71], 3, v[58:59]
	global_load_dwordx4 v[100:103], v[70:71], off
	global_load_dwordx4 v[104:107], v[70:71], off offset:16
	global_load_dwordx4 v[108:111], v[70:71], off offset:32
	global_load_dwordx4 v[112:115], v[70:71], off offset:48
	global_load_dwordx4 v[116:119], v[70:71], off offset:64
	global_load_dwordx4 v[120:123], v[70:71], off offset:80
	global_load_dwordx4 v[124:127], v[70:71], off offset:96
	global_load_dwordx4 v[128:131], v[70:71], off offset:112
	s_waitcnt vmcnt(0)
	s_cbranch_scc1 .LBB0_147
	s_waitcnt lgkmcnt(1)
	v_mul_f32_e32 v86, v72, v80
	s_waitcnt lgkmcnt(0)
	v_mul_f32_e32 v81, v72, v79
	v_mov_b32_e32 v80, v53
	s_waitcnt vmcnt(0)
	v_pk_mul_f32 v[80:81], v[80:81], v[102:103]
	v_mul_f32_e32 v52, v52, v100
	v_mul_f32_e32 v82, v86, v101
	v_mov_b32_e32 v53, v81
	v_mov_b32_e32 v83, v80
	v_pk_add_f32 v[52:53], v[52:53], v[82:83]
.LBB0_147:
	s_waitcnt lgkmcnt(1)
	v_mov_b32_dpp v80, v54 quad_perm:[2,3,0,1] row_mask:0xf bank_mask:0xf
	s_waitcnt lgkmcnt(1)
	v_mov_b32_dpp v79, v55 quad_perm:[2,3,0,1] row_mask:0xf bank_mask:0xf
	v_cndmask_b32_e64 v81, 0, 1, vcc
	v_cmp_ne_u32_e64 s[8:9], 1, v81
	s_andn2_b64 vcc, exec, vcc
	s_cbranch_vccnz .LBB0_149
	s_waitcnt lgkmcnt(1)
	v_mul_f32_e32 v86, v72, v80
	s_waitcnt lgkmcnt(0)
	v_mul_f32_e32 v81, v72, v79
	v_mov_b32_e32 v80, v55
	s_waitcnt vmcnt(0)
	v_pk_mul_f32 v[80:81], v[80:81], v[106:107]
	v_mul_f32_e32 v54, v54, v104
	v_mul_f32_e32 v82, v86, v105
	v_mov_b32_e32 v55, v81
	v_mov_b32_e32 v83, v80
	v_pk_add_f32 v[54:55], v[54:55], v[82:83]
.LBB0_149:
	s_waitcnt lgkmcnt(1)
	v_mov_b32_dpp v80, v66 quad_perm:[2,3,0,1] row_mask:0xf bank_mask:0xf
	s_waitcnt lgkmcnt(1)
	v_mov_b32_dpp v79, v67 quad_perm:[2,3,0,1] row_mask:0xf bank_mask:0xf
	s_and_b64 vcc, exec, s[8:9]
	s_cbranch_vccnz .LBB0_151
	s_waitcnt lgkmcnt(1)
	v_mul_f32_e32 v86, v72, v80
	s_waitcnt lgkmcnt(0)
	v_mul_f32_e32 v81, v72, v79
	v_mov_b32_e32 v80, v67
	s_waitcnt vmcnt(0)
	v_pk_mul_f32 v[80:81], v[80:81], v[110:111]
	v_mul_f32_e32 v66, v66, v108
	v_mul_f32_e32 v82, v86, v109
	v_mov_b32_e32 v67, v81
	v_mov_b32_e32 v83, v80
	v_pk_add_f32 v[66:67], v[66:67], v[82:83]
.LBB0_151:
	s_waitcnt lgkmcnt(1)
	v_mov_b32_dpp v80, v68 quad_perm:[2,3,0,1] row_mask:0xf bank_mask:0xf
	s_waitcnt lgkmcnt(1)
	v_mov_b32_dpp v79, v69 quad_perm:[2,3,0,1] row_mask:0xf bank_mask:0xf
	s_and_b64 vcc, exec, s[8:9]
	s_cbranch_vccnz .LBB0_153
	s_waitcnt lgkmcnt(1)
	v_mul_f32_e32 v86, v72, v80
	s_waitcnt lgkmcnt(0)
	v_mul_f32_e32 v81, v72, v79
	v_mov_b32_e32 v80, v69
	s_waitcnt vmcnt(0)
	v_pk_mul_f32 v[80:81], v[80:81], v[114:115]
	v_mul_f32_e32 v68, v68, v112
	v_mul_f32_e32 v82, v86, v113
	v_mov_b32_e32 v69, v81
	v_mov_b32_e32 v83, v80
	v_pk_add_f32 v[68:69], v[68:69], v[82:83]
.LBB0_153:
	s_waitcnt lgkmcnt(1)
	v_mov_b32_dpp v80, v44 quad_perm:[2,3,0,1] row_mask:0xf bank_mask:0xf
	s_waitcnt lgkmcnt(1)
	v_mov_b32_dpp v79, v45 quad_perm:[2,3,0,1] row_mask:0xf bank_mask:0xf
	s_and_b64 vcc, exec, s[8:9]
	s_cbranch_vccnz .LBB0_155
	s_waitcnt lgkmcnt(1)
	v_mul_f32_e32 v86, v72, v80
	s_waitcnt lgkmcnt(0)
	v_mul_f32_e32 v81, v72, v79
	v_mov_b32_e32 v80, v45
	s_waitcnt vmcnt(0)
	v_pk_mul_f32 v[80:81], v[80:81], v[118:119]
	v_mul_f32_e32 v44, v44, v116
	v_mul_f32_e32 v82, v86, v117
	v_mov_b32_e32 v45, v81
	v_mov_b32_e32 v83, v80
	v_pk_add_f32 v[44:45], v[44:45], v[82:83]
.LBB0_155:
	s_waitcnt lgkmcnt(1)
	v_mov_b32_dpp v80, v46 quad_perm:[2,3,0,1] row_mask:0xf bank_mask:0xf
	s_waitcnt lgkmcnt(1)
	v_mov_b32_dpp v79, v47 quad_perm:[2,3,0,1] row_mask:0xf bank_mask:0xf
	s_and_b64 vcc, exec, s[8:9]
	s_cbranch_vccnz .LBB0_157
	s_waitcnt lgkmcnt(1)
	v_mul_f32_e32 v86, v72, v80
	s_waitcnt lgkmcnt(0)
	v_mul_f32_e32 v81, v72, v79
	v_mov_b32_e32 v80, v47
	s_waitcnt vmcnt(0)
	v_pk_mul_f32 v[80:81], v[80:81], v[122:123]
	v_mul_f32_e32 v46, v46, v120
	v_mul_f32_e32 v82, v86, v121
	v_mov_b32_e32 v47, v81
	v_mov_b32_e32 v83, v80
	v_pk_add_f32 v[46:47], v[46:47], v[82:83]
.LBB0_157:
	s_waitcnt lgkmcnt(1)
	v_mov_b32_dpp v80, v50 quad_perm:[2,3,0,1] row_mask:0xf bank_mask:0xf
	s_waitcnt lgkmcnt(1)
	v_mov_b32_dpp v79, v51 quad_perm:[2,3,0,1] row_mask:0xf bank_mask:0xf
	s_and_b64 vcc, exec, s[8:9]
	s_cbranch_vccnz .LBB0_159
	s_waitcnt lgkmcnt(1)
	v_mul_f32_e32 v86, v72, v80
	s_waitcnt lgkmcnt(0)
	v_mul_f32_e32 v81, v72, v79
	v_mov_b32_e32 v80, v51
	s_waitcnt vmcnt(0)
	v_pk_mul_f32 v[80:81], v[80:81], v[126:127]
	v_mul_f32_e32 v50, v50, v124
	v_mul_f32_e32 v82, v86, v125
	v_mov_b32_e32 v51, v81
	v_mov_b32_e32 v83, v80
	v_pk_add_f32 v[50:51], v[50:51], v[82:83]
.LBB0_159:
	s_waitcnt lgkmcnt(1)
	v_mov_b32_dpp v80, v48 quad_perm:[2,3,0,1] row_mask:0xf bank_mask:0xf
	s_waitcnt lgkmcnt(1)
	v_mov_b32_dpp v79, v49 quad_perm:[2,3,0,1] row_mask:0xf bank_mask:0xf
	s_and_b64 vcc, exec, s[8:9]
	s_cbranch_vccnz .LBB0_161
	s_waitcnt lgkmcnt(0)
	v_mul_f32_e32 v71, v72, v79
	v_mov_b32_e32 v70, v49
	v_mul_f32_e32 v80, v72, v80
	s_waitcnt vmcnt(0)
	v_pk_mul_f32 v[70:71], v[70:71], v[130:131]
	v_mul_f32_e32 v48, v48, v128
	v_mul_f32_e32 v80, v80, v129
	v_mov_b32_e32 v49, v71
	v_mov_b32_e32 v81, v70
	v_pk_add_f32 v[48:49], v[48:49], v[80:81]

.LBB0_162:
	s_or_b64 exec, exec, s[12:13]
	s_waitcnt vmcnt(1)
	v_lshlrev_b32_e32 v46, 16, v43
	v_and_b32_e32 v47, 0xffff0000, v43
	s_mov_b32 s8, 0x3d372713
	v_pk_mul_f32 v[48:49], v[46:47], s[8:9] op_sel_hi:[1,0]
	s_mov_b32 s12, 0x3f4c422a
	v_pk_mul_f32 v[48:49], v[48:49], v[46:47]
	s_mov_b32 s1, 0x800000
	v_pk_fma_f32 v[48:49], v[48:49], v[46:47], v[46:47]
	v_pk_mul_f32 v[46:47], v[46:47], 0.5 op_sel_hi:[1,0]
	v_pk_mul_f32 v[48:49], v[48:49], s[12:13] op_sel_hi:[1,0]
	v_lshl_add_u64 v[44:45], s[2:3], 0, v[192:193]
	v_mul_f32_e64 v43, |v48|, -2.0
	v_mul_f32_e32 v43, 0x3fb8aa3b, v43
	v_exp_f32_e32 v50, v43
	v_mul_f32_e64 v43, |v49|, -2.0
	v_mul_f32_e32 v43, 0x3fb8aa3b, v43
	v_exp_f32_e32 v51, v43
	v_add_f32_e32 v43, 1.0, v50
	v_rcp_f32_e32 v52, v43
	v_cmp_gt_f32_e32 vcc, 0, v49
	v_add_f32_e32 v43, 1.0, v51
	v_rcp_f32_e32 v53, v43
	v_pk_add_f32 v[50:51], v[50:51], 1.0 op_sel_hi:[1,0] neg_lo:[1,0] neg_hi:[1,0]
	s_nop 0
	v_pk_mul_f32 v[50:51], v[50:51], v[52:53]
	v_lshlrev_b32_e32 v52, 16, v42
	v_and_b32_e32 v53, 0xffff0000, v42
	v_pk_mul_f32 v[54:55], v[52:53], s[8:9] op_sel_hi:[1,0]
	v_cndmask_b32_e64 v43, v51, -v51, vcc
	v_pk_mul_f32 v[54:55], v[54:55], v[52:53]
	v_cmp_gt_f32_e32 vcc, 0, v48
	v_pk_fma_f32 v[54:55], v[54:55], v[52:53], v[52:53]
	v_pk_mul_f32 v[52:53], v[52:53], 0.5 op_sel_hi:[1,0]
	v_pk_mul_f32 v[54:55], v[54:55], s[12:13] op_sel_hi:[1,0]
	s_nop 0
	v_mul_f32_e64 v42, |v54|, -2.0
	v_mul_f32_e32 v42, 0x3fb8aa3b, v42
	v_exp_f32_e32 v64, v42
	v_mul_f32_e64 v42, |v55|, -2.0
	v_mul_f32_e32 v42, 0x3fb8aa3b, v42
	v_exp_f32_e32 v65, v42
	v_add_f32_e32 v48, 1.0, v64
	v_rcp_f32_e32 v48, v48
	v_cndmask_b32_e64 v42, v50, -v50, vcc
	v_add_f32_e32 v49, 1.0, v65
	v_rcp_f32_e32 v49, v49
	v_pk_add_f32 v[64:65], v[64:65], 1.0 op_sel_hi:[1,0] neg_lo:[1,0] neg_hi:[1,0]
	v_cmp_gt_f32_e32 vcc, 0, v55
	v_pk_add_f32 v[42:43], v[42:43], 1.0 op_sel_hi:[1,0]
	v_pk_mul_f32 v[48:49], v[64:65], v[48:49]
	v_lshlrev_b32_e32 v64, 16, v41
	v_and_b32_e32 v65, 0xffff0000, v41
	v_pk_mul_f32 v[66:67], v[64:65], s[8:9] op_sel_hi:[1,0]
	v_cndmask_b32_e64 v49, v49, -v49, vcc
	v_pk_mul_f32 v[66:67], v[66:67], v[64:65]
	v_cmp_gt_f32_e32 vcc, 0, v54
	v_pk_fma_f32 v[66:67], v[66:67], v[64:65], v[64:65]
	v_pk_mul_f32 v[64:65], v[64:65], 0.5 op_sel_hi:[1,0]
	v_pk_mul_f32 v[66:67], v[66:67], s[12:13] op_sel_hi:[1,0]
	v_cndmask_b32_e64 v48, v48, -v48, vcc
	v_mul_f32_e64 v41, |v66|, -2.0
	v_mul_f32_e32 v41, 0x3fb8aa3b, v41
	v_exp_f32_e32 v68, v41
	v_mul_f32_e64 v41, |v67|, -2.0
	v_mul_f32_e32 v41, 0x3fb8aa3b, v41
	v_exp_f32_e32 v69, v41
	v_add_f32_e32 v41, 1.0, v68
	v_rcp_f32_e32 v54, v41
	v_cmp_gt_f32_e32 vcc, 0, v67
	v_add_f32_e32 v41, 1.0, v69
	v_rcp_f32_e32 v55, v41
	v_pk_add_f32 v[68:69], v[68:69], 1.0 op_sel_hi:[1,0] neg_lo:[1,0] neg_hi:[1,0]
	v_pk_add_f32 v[48:49], v[48:49], 1.0 op_sel_hi:[1,0]
	v_pk_mul_f32 v[50:51], v[46:47], v[42:43]
	v_pk_mul_f32 v[54:55], v[68:69], v[54:55]
	v_lshlrev_b32_e32 v68, 16, v40
	v_and_b32_e32 v69, 0xffff0000, v40
	s_waitcnt lgkmcnt(1)
	v_pk_mul_f32 v[80:81], v[68:69], s[8:9] op_sel_hi:[1,0]
	v_cndmask_b32_e64 v41, v55, -v55, vcc
	v_pk_mul_f32 v[80:81], v[80:81], v[68:69]
	v_cmp_gt_f32_e32 vcc, 0, v66
	v_pk_fma_f32 v[80:81], v[80:81], v[68:69], v[68:69]
	v_pk_mul_f32 v[68:69], v[68:69], 0.5 op_sel_hi:[1,0]
	v_pk_mul_f32 v[80:81], v[80:81], s[12:13] op_sel_hi:[1,0]
	v_pk_mul_f32 v[70:71], v[52:53], v[48:49]
	v_mul_f32_e64 v40, |v80|, -2.0
	v_mul_f32_e32 v40, 0x3fb8aa3b, v40
	v_exp_f32_e32 v82, v40
	v_mul_f32_e64 v40, |v81|, -2.0
	v_mul_f32_e32 v40, 0x3fb8aa3b, v40
	v_exp_f32_e32 v83, v40
	v_cndmask_b32_e64 v40, v54, -v54, vcc
	v_add_f32_e32 v54, 1.0, v82
	v_rcp_f32_e32 v54, v54
	v_add_f32_e32 v55, 1.0, v83
	v_rcp_f32_e32 v55, v55
	v_pk_add_f32 v[82:83], v[82:83], 1.0 op_sel_hi:[1,0] neg_lo:[1,0] neg_hi:[1,0]
	v_cmp_gt_f32_e32 vcc, 0, v81
	v_pk_add_f32 v[40:41], v[40:41], 1.0 op_sel_hi:[1,0]
	v_pk_mul_f32 v[54:55], v[82:83], v[54:55]
	v_pk_mul_f32 v[66:67], v[64:65], v[40:41]
	v_cndmask_b32_e64 v55, v55, -v55, vcc
	v_cmp_gt_f32_e32 vcc, 0, v80
	s_nop 1
	v_cndmask_b32_e64 v54, v54, -v54, vcc
	v_pk_add_f32 v[54:55], v[54:55], 1.0 op_sel_hi:[1,0]
	s_nop 0
	v_pk_mul_f32 v[80:81], v[68:69], v[54:55]
	s_waitcnt lgkmcnt(0)
	v_add_f32_e32 v79, 0, v80
	v_add_f32_e32 v79, v81, v79
	v_add_f32_e32 v66, v66, v79
	v_add_f32_e32 v66, v67, v66
	v_add_f32_e32 v66, v70, v66
	v_add_f32_e32 v66, v71, v66
	v_add_f32_e32 v50, v50, v66
	v_add_f32_e32 v50, v51, v50
	s_nop 1
	v_add_f32_dpp v50, v50, v50 quad_perm:[1,0,3,2] row_mask:0xf bank_mask:0xf
	s_nop 1
	v_add_f32_dpp v50, v50, v50 quad_perm:[2,3,0,1] row_mask:0xf bank_mask:0xf
	s_nop 1
	v_add_f32_dpp v50, v50, v50 row_half_mirror row_mask:0xf bank_mask:0xf
	s_nop 1
	v_add_f32_dpp v50, v50, v50 row_mirror row_mask:0xf bank_mask:0xf
	v_mov_b32_e32 v51, v50
	s_nop 1
	v_permlane16_swap_b32_e32 v51, v50
	v_add_f32_e32 v50, v50, v51
	v_mov_b32_e32 v51, v50
	s_nop 1
	v_permlane32_swap_b32_e32 v51, v50
	v_add_f32_e32 v50, v50, v51
	v_mul_f32_e32 v50, 0x3b000000, v50
	v_pk_fma_f32 v[54:55], v[68:69], v[54:55], v[50:51] op_sel_hi:[1,1,0] neg_lo:[0,0,1] neg_hi:[0,0,1]
	v_pk_fma_f32 v[40:41], v[64:65], v[40:41], v[50:51] op_sel_hi:[1,1,0] neg_lo:[0,0,1] neg_hi:[0,0,1]
	v_pk_mul_f32 v[66:67], v[54:55], v[54:55]
	v_pk_mul_f32 v[64:65], v[40:41], v[40:41]
	v_pk_fma_f32 v[48:49], v[52:53], v[48:49], v[50:51] op_sel_hi:[1,1,0] neg_lo:[0,0,1] neg_hi:[0,0,1]
	v_pk_fma_f32 v[42:43], v[46:47], v[42:43], v[50:51] op_sel_hi:[1,1,0] neg_lo:[0,0,1] neg_hi:[0,0,1]
	v_add_f32_e32 v50, v66, v67
	v_add_f32_e32 v50, v64, v50
	v_pk_mul_f32 v[52:53], v[48:49], v[48:49]
	v_add_f32_e32 v50, v65, v50
	v_add_f32_e32 v50, v52, v50
	v_pk_mul_f32 v[46:47], v[42:43], v[42:43]
	v_add_f32_e32 v50, v53, v50
	v_add_f32_e32 v46, v46, v50
	v_add_f32_e32 v46, v47, v46
	s_nop 1
	v_add_f32_dpp v46, v46, v46 quad_perm:[1,0,3,2] row_mask:0xf bank_mask:0xf
	s_nop 1
	v_add_f32_dpp v46, v46, v46 quad_perm:[2,3,0,1] row_mask:0xf bank_mask:0xf
	s_nop 1
	v_add_f32_dpp v46, v46, v46 row_half_mirror row_mask:0xf bank_mask:0xf
	s_nop 1
	v_add_f32_dpp v46, v46, v46 row_mirror row_mask:0xf bank_mask:0xf
	v_mov_b32_e32 v47, v46
	s_nop 1
	v_permlane16_swap_b32_e32 v47, v46
	v_add_f32_e32 v46, v46, v47
	v_mov_b32_e32 v47, v46
	s_nop 1
	v_permlane32_swap_b32_e32 v47, v46
	v_add_f32_e32 v46, v46, v47
	v_fmamk_f32 v46, v46, 0x3b000000, v225
	v_mul_f32_e32 v47, 0x4b800000, v46
	v_cmp_gt_f32_e32 vcc, s1, v46
	s_nop 1
	v_cndmask_b32_e32 v46, v46, v47, vcc
	v_rsq_f32_e32 v46, v46
	s_nop 0
	v_mul_f32_e32 v47, 0x45800000, v46
	v_cndmask_b32_e32 v46, v46, v47, vcc
	v_pk_mul_f32 v[40:41], v[40:41], v[46:47] op_sel_hi:[1,0]
	v_pk_mul_f32 v[50:51], v[54:55], v[46:47] op_sel_hi:[1,0]
	v_pk_fma_f32 v[52:53], v[10:11], v[40:41], v[14:15]
	v_pk_mul_f32 v[40:41], v[48:49], v[46:47] op_sel_hi:[1,0]
	v_pk_fma_f32 v[50:51], v[8:9], v[50:51], v[12:13]
	v_pk_fma_f32 v[48:49], v[0:1], v[40:41], v[4:5]
	v_pk_mul_f32 v[40:41], v[42:43], v[46:47] op_sel_hi:[1,0]
	v_cvt_pk_bf16_f32 v42, v48, v49
	v_pk_fma_f32 v[46:47], v[2:3], v[40:41], v[6:7]
	v_cvt_pk_bf16_f32 v40, v50, v51
	v_cvt_pk_bf16_f32 v41, v52, v53
	v_cvt_pk_bf16_f32 v43, v46, v47
	global_store_dwordx4 v[44:45], v[40:43], off offset:1024
	s_and_saveexec_b64 s[12:13], s[4:5]
	s_cbranch_execz .LBB0_139
	v_lshlrev_b32_e32 v40, 16, v36
	v_and_b32_e32 v41, 0xffff0000, v36
	v_pk_mul_f32 v[42:43], v[40:41], v[40:41]
	v_lshlrev_b32_e32 v36, 16, v37
	v_and_b32_e32 v37, 0xffff0000, v37
	v_pk_mul_f32 v[44:45], v[36:37], v[36:37]
	v_add_f32_e32 v42, v42, v43
	v_lshlrev_b32_e32 v46, 16, v38
	v_and_b32_e32 v47, 0xffff0000, v38
	v_add_f32_e32 v42, v44, v42
	v_pk_mul_f32 v[48:49], v[46:47], v[46:47]
	v_add_f32_e32 v42, v45, v42
	v_lshlrev_b32_e32 v38, 16, v39
	v_and_b32_e32 v39, 0xffff0000, v39
	v_add_f32_e32 v42, v48, v42
	v_pk_mul_f32 v[50:51], v[38:39], v[38:39]
	v_add_f32_e32 v42, v49, v42
	v_lshlrev_b32_e32 v52, 16, v32
	v_and_b32_e32 v53, 0xffff0000, v32
	v_add_f32_e32 v42, v50, v42
	v_pk_mul_f32 v[54:55], v[52:53], v[52:53]
	v_add_f32_e32 v42, v51, v42
	v_lshlrev_b32_e32 v64, 16, v33
	v_and_b32_e32 v65, 0xffff0000, v33
	v_add_f32_e32 v42, v54, v42
	v_pk_mul_f32 v[32:33], v[64:65], v[64:65]
	v_add_f32_e32 v42, v55, v42
	v_lshlrev_b32_e32 v66, 16, v34
	v_and_b32_e32 v67, 0xffff0000, v34
	v_add_f32_e32 v32, v32, v42
	v_pk_mul_f32 v[68:69], v[66:67], v[66:67]
	v_add_f32_e32 v32, v33, v32
	v_lshlrev_b32_e32 v70, 16, v35
	v_and_b32_e32 v71, 0xffff0000, v35
	v_add_f32_e32 v32, v68, v32
	v_pk_mul_f32 v[34:35], v[70:71], v[70:71]
	v_add_f32_e32 v32, v69, v32
	v_add_f32_e32 v32, v34, v32
	v_add_f32_e32 v32, v35, v32
	s_mov_b32 s9, 0x800000
	s_mul_hi_i32 s1, s10, 0x38e38e39
	s_lshr_b32 s8, s1, 31
	s_ashr_i32 s1, s1, 9
	s_nop 1
	v_add_f32_dpp v32, v32, v32 quad_perm:[1,0,3,2] row_mask:0xf bank_mask:0xf
	s_add_i32 s1, s1, s8
	s_mulk_i32 s1, 0x900
	s_sub_i32 s1, s10, s1
	s_cmpk_gt_i32 s1, 0xff
	s_nop 1
	v_add_f32_dpp v32, v32, v32 quad_perm:[2,3,0,1] row_mask:0xf bank_mask:0xf
	s_nop 1
	v_add_f32_dpp v32, v32, v32 row_half_mirror row_mask:0xf bank_mask:0xf
	v_fmamk_f32 v32, v32, 0x3c000000, v225
	v_mul_f32_e32 v33, 0x4b800000, v32
	v_cmp_gt_f32_e32 vcc, s9, v32
	s_nop 1
	v_cndmask_b32_e32 v32, v32, v33, vcc
	v_rsq_f32_e32 v32, v32
	s_nop 0
	v_mul_f32_e32 v33, 0x45800000, v32
	v_cndmask_b32_e32 v48, v32, v33, vcc
	v_pk_mul_f32 v[32:33], v[48:49], v[40:41] op_sel_hi:[0,1]
	v_pk_mul_f32 v[34:35], v[28:29], v[32:33]
	v_pk_mul_f32 v[32:33], v[48:49], v[36:37] op_sel_hi:[0,1]
	v_pk_mul_f32 v[42:43], v[30:31], v[32:33]
	v_pk_mul_f32 v[32:33], v[48:49], v[46:47] op_sel_hi:[0,1]
	s_cselect_b64 vcc, -1, 0
	s_add_i32 s8, s1, 0xffffff00
	v_pk_mul_f32 v[44:45], v[24:25], v[32:33]
	v_pk_mul_f32 v[32:33], v[48:49], v[38:39] op_sel_hi:[0,1]
	v_pk_mul_f32 v[38:39], v[48:49], v[66:67] op_sel_hi:[0,1]
	s_and_b32 s9, s1, 63
	s_ashr_i32 s8, s8, 6
	v_pk_mul_f32 v[46:47], v[26:27], v[32:33]
	v_pk_mul_f32 v[32:33], v[48:49], v[52:53] op_sel_hi:[0,1]
	v_pk_mul_f32 v[36:37], v[48:49], v[64:65] op_sel_hi:[0,1]
	v_pk_mul_f32 v[40:41], v[16:17], v[38:39]
	v_pk_mul_f32 v[38:39], v[48:49], v[70:71] op_sel_hi:[0,1]
	v_mov_b32_e32 v48, s9
	v_mov_b32_e32 v49, s8
	v_cndmask_b32_e64 v48, v48, v49, s[6:7]
	v_mov_b32_dpp v51, v34 quad_perm:[2,3,0,1] row_mask:0xf bank_mask:0xf
	v_mov_b32_dpp v50, v35 quad_perm:[2,3,0,1] row_mask:0xf bank_mask:0xf
	v_lshlrev_b32_e32 v48, 5, v48
	v_cndmask_b32_e32 v48, 0, v48, vcc
	v_ashrrev_i32_e32 v49, 31, v48
	v_pk_mul_f32 v[32:33], v[20:21], v[32:33]
	v_pk_mul_f32 v[36:37], v[22:23], v[36:37]
	v_pk_mul_f32 v[38:39], v[18:19], v[38:39]
	s_cmpk_lt_i32 s1, 0x100
	v_lshl_add_u64 v[48:49], v[48:49], 3, v[58:59]
	global_load_dwordx4 v[132:135], v[48:49], off
	global_load_dwordx4 v[136:139], v[48:49], off offset:16
	global_load_dwordx4 v[140:143], v[48:49], off offset:32
	global_load_dwordx4 v[144:147], v[48:49], off offset:48
	global_load_dwordx4 v[148:151], v[48:49], off offset:64
	global_load_dwordx4 v[152:155], v[48:49], off offset:80
	global_load_dwordx4 v[156:159], v[48:49], off offset:96
	global_load_dwordx4 v[160:163], v[48:49], off offset:112
	s_waitcnt vmcnt(0)
	s_cbranch_scc1 .LBB0_165
	s_waitcnt lgkmcnt(1)
	v_mul_f32_e32 v64, v72, v51
	s_waitcnt lgkmcnt(0)
	v_mul_f32_e32 v51, v72, v50
	v_mov_b32_e32 v50, v35
	s_waitcnt vmcnt(0)
	v_pk_mul_f32 v[50:51], v[50:51], v[134:135]
	v_mul_f32_e32 v34, v34, v132
	v_mul_f32_e32 v52, v64, v133
	v_mov_b32_e32 v35, v51
	v_mov_b32_e32 v53, v50
	v_pk_add_f32 v[34:35], v[34:35], v[52:53]
.LBB0_165:
	s_waitcnt lgkmcnt(1)
	v_mov_b32_dpp v51, v42 quad_perm:[2,3,0,1] row_mask:0xf bank_mask:0xf
	s_waitcnt lgkmcnt(1)
	v_mov_b32_dpp v50, v43 quad_perm:[2,3,0,1] row_mask:0xf bank_mask:0xf
	v_cndmask_b32_e64 v52, 0, 1, vcc
	v_cmp_ne_u32_e64 s[8:9], 1, v52
	s_andn2_b64 vcc, exec, vcc
	s_cbranch_vccnz .LBB0_167
	s_waitcnt lgkmcnt(1)
	v_mul_f32_e32 v64, v72, v51
	s_waitcnt lgkmcnt(0)
	v_mul_f32_e32 v51, v72, v50
	v_mov_b32_e32 v50, v43
	s_waitcnt vmcnt(0)
	v_pk_mul_f32 v[50:51], v[50:51], v[138:139]
	v_mul_f32_e32 v42, v42, v136
	v_mul_f32_e32 v52, v64, v137
	v_mov_b32_e32 v43, v51
	v_mov_b32_e32 v53, v50
	v_pk_add_f32 v[42:43], v[42:43], v[52:53]
.LBB0_167:
	s_waitcnt lgkmcnt(1)
	v_mov_b32_dpp v51, v44 quad_perm:[2,3,0,1] row_mask:0xf bank_mask:0xf
	s_waitcnt lgkmcnt(1)
	v_mov_b32_dpp v50, v45 quad_perm:[2,3,0,1] row_mask:0xf bank_mask:0xf
	s_and_b64 vcc, exec, s[8:9]
	s_cbranch_vccnz .LBB0_169
	s_waitcnt lgkmcnt(1)
	v_mul_f32_e32 v64, v72, v51
	s_waitcnt lgkmcnt(0)
	v_mul_f32_e32 v51, v72, v50
	v_mov_b32_e32 v50, v45
	s_waitcnt vmcnt(0)
	v_pk_mul_f32 v[50:51], v[50:51], v[142:143]
	v_mul_f32_e32 v44, v44, v140
	v_mul_f32_e32 v52, v64, v141
	v_mov_b32_e32 v45, v51
	v_mov_b32_e32 v53, v50
	v_pk_add_f32 v[44:45], v[44:45], v[52:53]
.LBB0_169:
	s_waitcnt lgkmcnt(1)
	v_mov_b32_dpp v51, v46 quad_perm:[2,3,0,1] row_mask:0xf bank_mask:0xf
	s_waitcnt lgkmcnt(1)
	v_mov_b32_dpp v50, v47 quad_perm:[2,3,0,1] row_mask:0xf bank_mask:0xf
	s_and_b64 vcc, exec, s[8:9]
	s_cbranch_vccnz .LBB0_171
	s_waitcnt lgkmcnt(1)
	v_mul_f32_e32 v64, v72, v51
	s_waitcnt lgkmcnt(0)
	v_mul_f32_e32 v51, v72, v50
	v_mov_b32_e32 v50, v47
	s_waitcnt vmcnt(0)
	v_pk_mul_f32 v[50:51], v[50:51], v[146:147]
	v_mul_f32_e32 v46, v46, v144
	v_mul_f32_e32 v52, v64, v145
	v_mov_b32_e32 v47, v51
	v_mov_b32_e32 v53, v50
	v_pk_add_f32 v[46:47], v[46:47], v[52:53]
.LBB0_171:
	s_waitcnt lgkmcnt(1)
	v_mov_b32_dpp v51, v32 quad_perm:[2,3,0,1] row_mask:0xf bank_mask:0xf
	s_waitcnt lgkmcnt(1)
	v_mov_b32_dpp v50, v33 quad_perm:[2,3,0,1] row_mask:0xf bank_mask:0xf
	s_and_b64 vcc, exec, s[8:9]
	s_cbranch_vccnz .LBB0_173
	s_waitcnt lgkmcnt(1)
	v_mul_f32_e32 v64, v72, v51
	s_waitcnt lgkmcnt(0)
	v_mul_f32_e32 v51, v72, v50
	v_mov_b32_e32 v50, v33
	s_waitcnt vmcnt(0)
	v_pk_mul_f32 v[50:51], v[50:51], v[150:151]
	v_mul_f32_e32 v32, v32, v148
	v_mul_f32_e32 v52, v64, v149
	v_mov_b32_e32 v33, v51
	v_mov_b32_e32 v53, v50
	v_pk_add_f32 v[32:33], v[32:33], v[52:53]
.LBB0_173:
	s_waitcnt lgkmcnt(1)
	v_mov_b32_dpp v51, v36 quad_perm:[2,3,0,1] row_mask:0xf bank_mask:0xf
	s_waitcnt lgkmcnt(1)
	v_mov_b32_dpp v50, v37 quad_perm:[2,3,0,1] row_mask:0xf bank_mask:0xf
	s_and_b64 vcc, exec, s[8:9]
	s_cbranch_vccnz .LBB0_175
	s_waitcnt lgkmcnt(1)
	v_mul_f32_e32 v64, v72, v51
	s_waitcnt lgkmcnt(0)
	v_mul_f32_e32 v51, v72, v50
	v_mov_b32_e32 v50, v37
	s_waitcnt vmcnt(0)
	v_pk_mul_f32 v[50:51], v[50:51], v[154:155]
	v_mul_f32_e32 v36, v36, v152
	v_mul_f32_e32 v52, v64, v153
	v_mov_b32_e32 v37, v51
	v_mov_b32_e32 v53, v50
	v_pk_add_f32 v[36:37], v[36:37], v[52:53]
.LBB0_175:
	s_waitcnt lgkmcnt(1)
	v_mov_b32_dpp v51, v40 quad_perm:[2,3,0,1] row_mask:0xf bank_mask:0xf
	s_waitcnt lgkmcnt(1)
	v_mov_b32_dpp v50, v41 quad_perm:[2,3,0,1] row_mask:0xf bank_mask:0xf
	s_and_b64 vcc, exec, s[8:9]
	s_cbranch_vccnz .LBB0_177
	s_waitcnt lgkmcnt(1)
	v_mul_f32_e32 v64, v72, v51
	s_waitcnt lgkmcnt(0)
	v_mul_f32_e32 v51, v72, v50
	v_mov_b32_e32 v50, v41
	s_waitcnt vmcnt(0)
	v_pk_mul_f32 v[50:51], v[50:51], v[158:159]
	v_mul_f32_e32 v40, v40, v156
	v_mul_f32_e32 v52, v64, v157
	v_mov_b32_e32 v41, v51
	v_mov_b32_e32 v53, v50
	v_pk_add_f32 v[40:41], v[40:41], v[52:53]
.LBB0_177:
	s_waitcnt lgkmcnt(1)
	v_mov_b32_dpp v51, v38 quad_perm:[2,3,0,1] row_mask:0xf bank_mask:0xf
	s_waitcnt lgkmcnt(1)
	v_mov_b32_dpp v50, v39 quad_perm:[2,3,0,1] row_mask:0xf bank_mask:0xf
	s_and_b64 vcc, exec, s[8:9]
	s_cbranch_vccnz .LBB0_138
	s_waitcnt lgkmcnt(0)
	v_mul_f32_e32 v49, v72, v50
	v_mov_b32_e32 v48, v39
	v_mul_f32_e32 v51, v72, v51
	s_waitcnt vmcnt(0)
	v_pk_mul_f32 v[48:49], v[48:49], v[162:163]
	v_mul_f32_e32 v38, v38, v160
	v_mul_f32_e32 v50, v51, v161
	v_mov_b32_e32 v39, v49
	v_mov_b32_e32 v51, v48
	v_pk_add_f32 v[38:39], v[38:39], v[50:51]
	s_branch .LBB0_138
